# attention: after a subtile was skipped, farther subtiles run a short body first (QK^T + row maxima + the same exact-zero test) and fall back to the general recompute path only if the test fails
# speedup vs baseline: 1.0204x; 1.0112x over previous
.LBB0_738:
	s_mov_b32 s36, s50
	s_mov_b32 s51, 0

.LBB0_763:
	s_cmp_lg_u32 s51, 0
	s_cbranch_scc1 .Lat1_probe
	ds_read_b128 v[160:163], v237 offset:8192
	ds_read_b128 v[164:167], v189
	ds_read_b128 v[202:205], v235 offset:8192
	ds_read_b128 v[244:247], v189 offset:4096
	ds_read_b128 v[248:251], v236 offset:8192
	ds_read_b128 v[252:255], v189 offset:1024
	s_cmp_lg_u32 s79, s40
	s_waitcnt lgkmcnt(4)
	v_mfma_f32_32x32x16_bf16 v[144:159], v[160:163], v[164:167], v[128:143]
	s_waitcnt lgkmcnt(2)
	v_mfma_f32_32x32x16_bf16 v[160:175], v[202:205], v[244:247], v[128:143]
	ds_read_b128 v[202:205], v234 offset:8192
	ds_read_b128 v[244:247], v189 offset:5120
	v_add_u32_e32 v215, s40, v185
	v_add_u32_e32 v215, 0xe0, v215
	v_cvt_f32_i32_e32 v215, v215
	v_add_f32_e32 v227, 0x41000000, v199
	v_mul_f32_e32 v200, v184, v215
	v_add_f32_e32 v215, 0x41000000, v201
	s_waitcnt lgkmcnt(2)
	v_mfma_f32_32x32x16_bf16 v[144:159], v[248:251], v[252:255], v[144:159]
	ds_read_b128 v[248:251], v241 offset:8192
	ds_read_b128 v[252:255], v189 offset:2048
	s_waitcnt lgkmcnt(2)
	v_mfma_f32_32x32x16_bf16 v[160:175], v[202:205], v[244:247], v[160:175]
	ds_read_b128 v[202:205], v239 offset:8192
	ds_read_b128 v[244:247], v189 offset:6144
	s_waitcnt lgkmcnt(2)
	v_mfma_f32_32x32x16_bf16 v[144:159], v[248:251], v[252:255], v[144:159]
	ds_read_b128 v[248:251], v240 offset:8192
	ds_read_b128 v[252:255], v189 offset:3072
	s_waitcnt lgkmcnt(2)
	v_mfma_f32_32x32x16_bf16 v[160:175], v[202:205], v[244:247], v[160:175]
	ds_read_b128 v[202:205], v238 offset:8192
	ds_read_b128 v[244:247], v189 offset:7168
	s_waitcnt lgkmcnt(2)
	v_mfma_f32_32x32x16_bf16 v[144:159], v[248:251], v[252:255], v[144:159]
	s_waitcnt lgkmcnt(0)
	v_mfma_f32_32x32x16_bf16 v[160:175], v[202:205], v[244:247], v[160:175]
	ds_read_b64_tr_b16 v[202:203], v216 offset:8192
	ds_read_b64_tr_b16 v[204:205], v218 offset:8192
	ds_read_b64_tr_b16 v[244:245], v220 offset:8192
	ds_read_b64_tr_b16 v[246:247], v222 offset:8192
	ds_read_b64_tr_b16 v[248:249], v224 offset:8192
	ds_read_b64_tr_b16 v[250:251], v226 offset:8192
	ds_read_b64_tr_b16 v[252:253], v228 offset:8192
	ds_read_b64_tr_b16 v[254:255], v230 offset:8192
	s_cbranch_scc0 .Lat1_diag
.Lat1_go:
	v_sub_f32_e32 v180, v200, v199
	v_sub_f32_e32 v198, v200, v201
	s_nop 0
	v_max3_f32 v217, v144, v145, v146
	v_max3_f32 v219, v160, v161, v162
	v_max3_f32 v221, v147, v148, v149
	v_max3_f32 v225, v163, v164, v165
	v_max3_f32 v223, v150, v151, v152
	v_max3_f32 v229, v166, v167, v168
	v_add_f32_e32 v144, v144, v180
	v_add_f32_e32 v160, v160, v198
	v_max3_f32 v217, v217, v221, v223
	v_exp_f32_e32 v144, v144
	v_exp_f32_e32 v160, v160
	v_max3_f32 v219, v219, v225, v229
	v_add_f32_e32 v145, v145, v180
	v_add_f32_e32 v161, v161, v198
	v_max3_f32 v221, v153, v154, v155
	v_exp_f32_e32 v145, v145
	v_exp_f32_e32 v161, v161
	v_max3_f32 v225, v169, v170, v171
	v_add_f32_e32 v146, v146, v180
	v_add_f32_e32 v162, v162, v198
	v_max3_f32 v223, v156, v157, v158
	v_exp_f32_e32 v146, v146
	v_exp_f32_e32 v162, v162
	v_max3_f32 v229, v172, v173, v174
	v_add_f32_e32 v147, v147, v180
	v_add_f32_e32 v163, v163, v198
	v_max3_f32 v221, v221, v223, v159
	v_exp_f32_e32 v147, v147
	v_exp_f32_e32 v163, v163
	v_max3_f32 v225, v225, v229, v175
	v_add_f32_e32 v148, v148, v180
	v_add_f32_e32 v164, v164, v198
	v_max_f32_e32 v217, v217, v221
	v_exp_f32_e32 v148, v148
	v_exp_f32_e32 v164, v164
	v_max_f32_e32 v219, v219, v225
	v_add_f32_e32 v149, v149, v180
	v_add_f32_e32 v165, v165, v198
	v_add_f32_e32 v221, v200, v217
	v_exp_f32_e32 v149, v149
	v_exp_f32_e32 v165, v165
	v_add_f32_e32 v225, v200, v219
	v_add_f32_e32 v150, v150, v180
	v_add_f32_e32 v166, v166, v198
	v_cmp_gt_f32_e32 vcc, v221, v227
	v_exp_f32_e32 v150, v150
	v_exp_f32_e32 v166, v166
	v_cmp_gt_f32_e64 s[0:1], v225, v215
	v_sub_f32_e32 v223, v221, v227
	v_sub_f32_e32 v229, v225, v215
	v_max_f32_e32 v223, v223, v229
	v_add_f32_e32 v223, 0x43280000, v223
	v_cmp_nlt_f32_e64 s[98:99], v223, 0
	v_add_f32_e32 v151, v151, v180
	v_add_f32_e32 v167, v167, v198
	v_exp_f32_e32 v151, v151
	v_exp_f32_e32 v167, v167
	v_add_f32_e32 v215, v144, v145
	v_add_f32_e32 v217, v160, v161
	v_add_f32_e32 v215, v215, v146
	v_add_f32_e32 v217, v217, v162
	v_add_f32_e32 v215, v215, v147
	v_add_f32_e32 v217, v217, v163
	v_add_f32_e32 v215, v215, v148
	v_add_f32_e32 v217, v217, v164
	v_add_f32_e32 v215, v215, v149
	v_add_f32_e32 v217, v217, v165
	v_add_f32_e32 v215, v215, v150
	v_add_f32_e32 v217, v217, v166
	v_add_f32_e32 v215, v215, v151
	v_add_f32_e32 v217, v217, v167
	v_cvt_pk_bf16_f32 v144, v144, v145
	v_cvt_pk_bf16_f32 v160, v160, v161
	v_cvt_pk_bf16_f32 v145, v146, v147
	v_cvt_pk_bf16_f32 v161, v162, v163
	v_cvt_pk_bf16_f32 v146, v148, v149
	v_cvt_pk_bf16_f32 v162, v164, v165
	v_cvt_pk_bf16_f32 v147, v150, v151
	v_cvt_pk_bf16_f32 v163, v166, v167
	ds_read_b64_tr_b16 v[148:149], v216 offset:12288
	ds_read_b64_tr_b16 v[150:151], v218 offset:12288
	ds_read_b64_tr_b16 v[164:165], v220 offset:12288
	ds_read_b64_tr_b16 v[166:167], v222 offset:12288
	s_or_b64 vcc, vcc, s[0:1]
	s_cbranch_vccnz .Lat1_redo
	s_cmp_eq_u64 s[98:99], 0
	s_cselect_b32 s51, 1, 0
	s_cbranch_scc1 .Lat1_skip
	s_waitcnt lgkmcnt(4)
	v_mfma_f32_32x32x16_bf16 v[112:127], v[202:205], v[144:147], v[112:127]
	v_add_f32_e32 v152, v152, v180
	v_add_f32_e32 v168, v168, v198
	v_exp_f32_e32 v152, v152
	v_exp_f32_e32 v168, v168
	v_mfma_f32_32x32x16_bf16 v[96:111], v[202:205], v[160:163], v[96:111]
	v_add_f32_e32 v153, v153, v180
	v_add_f32_e32 v169, v169, v198
	v_exp_f32_e32 v153, v153
	v_exp_f32_e32 v169, v169
	ds_read_b64_tr_b16 v[202:203], v224 offset:12288
	ds_read_b64_tr_b16 v[204:205], v226 offset:12288
	v_mfma_f32_32x32x16_bf16 v[64:79], v[244:247], v[144:147], v[64:79]
	v_add_f32_e32 v154, v154, v180
	v_add_f32_e32 v170, v170, v198
	v_exp_f32_e32 v154, v154
	v_exp_f32_e32 v170, v170
	v_mfma_f32_32x32x16_bf16 v[80:95], v[244:247], v[160:163], v[80:95]
	v_add_f32_e32 v155, v155, v180
	v_add_f32_e32 v171, v171, v198
	v_exp_f32_e32 v155, v155
	v_exp_f32_e32 v171, v171
	ds_read_b64_tr_b16 v[244:245], v228 offset:12288
	ds_read_b64_tr_b16 v[246:247], v230 offset:12288
	v_mfma_f32_32x32x16_bf16 v[32:47], v[248:251], v[144:147], v[32:47]
	v_add_f32_e32 v156, v156, v180
	v_add_f32_e32 v172, v172, v198
	v_exp_f32_e32 v156, v156
	v_exp_f32_e32 v172, v172
	v_mfma_f32_32x32x16_bf16 v[48:63], v[248:251], v[160:163], v[48:63]
	v_add_f32_e32 v157, v157, v180
	v_add_f32_e32 v173, v173, v198
	v_exp_f32_e32 v157, v157
	v_exp_f32_e32 v173, v173
	v_mfma_f32_32x32x16_bf16 v[0:15], v[252:255], v[144:147], v[0:15]
	v_add_f32_e32 v158, v158, v180
	v_add_f32_e32 v174, v174, v198
	v_exp_f32_e32 v158, v158
	v_exp_f32_e32 v174, v174
	v_mfma_f32_32x32x16_bf16 v[16:31], v[252:255], v[160:163], v[16:31]
	v_add_f32_e32 v159, v159, v180
	v_add_f32_e32 v175, v175, v198
	v_exp_f32_e32 v159, v159
	v_exp_f32_e32 v175, v175
	v_cvt_pk_bf16_f32 v248, v152, v153
	v_cvt_pk_bf16_f32 v252, v168, v169
	v_cvt_pk_bf16_f32 v249, v154, v155
	v_cvt_pk_bf16_f32 v253, v170, v171
	v_cvt_pk_bf16_f32 v250, v156, v157
	v_cvt_pk_bf16_f32 v254, v172, v173
	v_cvt_pk_bf16_f32 v251, v158, v159
	v_cvt_pk_bf16_f32 v255, v174, v175
	s_nop 0
	s_waitcnt lgkmcnt(6)
	v_mfma_f32_32x32x16_bf16 v[112:127], v[148:151], v[248:251], v[112:127]
	v_add_f32_e32 v215, v215, v152
	v_add_f32_e32 v217, v217, v168
	v_mfma_f32_32x32x16_bf16 v[96:111], v[148:151], v[252:255], v[96:111]
	v_add_f32_e32 v215, v215, v153
	v_add_f32_e32 v217, v217, v169
	v_add_f32_e32 v215, v215, v154
	s_waitcnt lgkmcnt(4)
	v_mfma_f32_32x32x16_bf16 v[64:79], v[164:167], v[248:251], v[64:79]
	v_add_f32_e32 v217, v217, v170
	v_add_f32_e32 v215, v215, v155
	v_mfma_f32_32x32x16_bf16 v[80:95], v[164:167], v[252:255], v[80:95]
	v_add_f32_e32 v217, v217, v171
	v_add_f32_e32 v215, v215, v156
	v_add_f32_e32 v217, v217, v172
	s_waitcnt lgkmcnt(2)
	v_mfma_f32_32x32x16_bf16 v[32:47], v[202:205], v[248:251], v[32:47]
	v_add_f32_e32 v215, v215, v157
	v_add_f32_e32 v217, v217, v173
	v_mfma_f32_32x32x16_bf16 v[48:63], v[202:205], v[252:255], v[48:63]
	v_add_f32_e32 v215, v215, v158
	v_add_f32_e32 v217, v217, v174
	v_add_f32_e32 v215, v215, v159
	s_waitcnt lgkmcnt(0)
	v_mfma_f32_32x32x16_bf16 v[0:15], v[244:247], v[248:251], v[0:15]
	v_add_f32_e32 v217, v217, v175
	v_add_f32_e32 v197, v197, v215
	v_mfma_f32_32x32x16_bf16 v[16:31], v[244:247], v[252:255], v[16:31]
	v_add_f32_e32 v196, v196, v217

.LBB0_768:
	s_cmp_lg_u32 s51, 0
	s_cbranch_scc1 .Lat2_probe
	ds_read_b128 v[160:163], v237
	ds_read_b128 v[164:167], v189
	ds_read_b128 v[202:205], v235
	ds_read_b128 v[244:247], v189 offset:4096
	ds_read_b128 v[248:251], v236
	ds_read_b128 v[252:255], v189 offset:1024
	s_cmp_lg_u32 s67, s40
	s_waitcnt lgkmcnt(4)
	v_mfma_f32_32x32x16_bf16 v[144:159], v[160:163], v[164:167], v[128:143]
	s_waitcnt lgkmcnt(2)
	v_mfma_f32_32x32x16_bf16 v[160:175], v[202:205], v[244:247], v[128:143]
	ds_read_b128 v[202:205], v234
	ds_read_b128 v[244:247], v189 offset:5120
	v_add_u32_e32 v215, s40, v185
	v_add_u32_e32 v215, 0xc0, v215
	v_cvt_f32_i32_e32 v215, v215
	v_add_f32_e32 v227, 0x41000000, v199
	v_mul_f32_e32 v200, v184, v215
	v_add_f32_e32 v215, 0x41000000, v201
	s_waitcnt lgkmcnt(2)
	v_mfma_f32_32x32x16_bf16 v[144:159], v[248:251], v[252:255], v[144:159]
	ds_read_b128 v[248:251], v241
	ds_read_b128 v[252:255], v189 offset:2048
	s_waitcnt lgkmcnt(2)
	v_mfma_f32_32x32x16_bf16 v[160:175], v[202:205], v[244:247], v[160:175]
	ds_read_b128 v[202:205], v239
	ds_read_b128 v[244:247], v189 offset:6144
	s_waitcnt lgkmcnt(2)
	v_mfma_f32_32x32x16_bf16 v[144:159], v[248:251], v[252:255], v[144:159]
	ds_read_b128 v[248:251], v240
	ds_read_b128 v[252:255], v189 offset:3072
	s_waitcnt lgkmcnt(2)
	v_mfma_f32_32x32x16_bf16 v[160:175], v[202:205], v[244:247], v[160:175]
	ds_read_b128 v[202:205], v238
	ds_read_b128 v[244:247], v189 offset:7168
	s_waitcnt lgkmcnt(2)
	v_mfma_f32_32x32x16_bf16 v[144:159], v[248:251], v[252:255], v[144:159]
	s_waitcnt lgkmcnt(0)
	v_mfma_f32_32x32x16_bf16 v[160:175], v[202:205], v[244:247], v[160:175]
	ds_read_b64_tr_b16 v[202:203], v216
	ds_read_b64_tr_b16 v[204:205], v218
	ds_read_b64_tr_b16 v[244:245], v220
	ds_read_b64_tr_b16 v[246:247], v222
	ds_read_b64_tr_b16 v[248:249], v224
	ds_read_b64_tr_b16 v[250:251], v226
	ds_read_b64_tr_b16 v[252:253], v228
	ds_read_b64_tr_b16 v[254:255], v230
	s_cbranch_scc0 .Lat2_diag
.Lat2_go:
	v_sub_f32_e32 v180, v200, v199
	v_sub_f32_e32 v198, v200, v201
	s_nop 0
	v_max3_f32 v217, v144, v145, v146
	v_max3_f32 v219, v160, v161, v162
	v_max3_f32 v221, v147, v148, v149
	v_max3_f32 v225, v163, v164, v165
	v_max3_f32 v223, v150, v151, v152
	v_max3_f32 v229, v166, v167, v168
	v_add_f32_e32 v144, v144, v180
	v_add_f32_e32 v160, v160, v198
	v_max3_f32 v217, v217, v221, v223
	v_exp_f32_e32 v144, v144
	v_exp_f32_e32 v160, v160
	v_max3_f32 v219, v219, v225, v229
	v_add_f32_e32 v145, v145, v180
	v_add_f32_e32 v161, v161, v198
	v_max3_f32 v221, v153, v154, v155
	v_exp_f32_e32 v145, v145
	v_exp_f32_e32 v161, v161
	v_max3_f32 v225, v169, v170, v171
	v_add_f32_e32 v146, v146, v180
	v_add_f32_e32 v162, v162, v198
	v_max3_f32 v223, v156, v157, v158
	v_exp_f32_e32 v146, v146
	v_exp_f32_e32 v162, v162
	v_max3_f32 v229, v172, v173, v174
	v_add_f32_e32 v147, v147, v180
	v_add_f32_e32 v163, v163, v198
	v_max3_f32 v221, v221, v223, v159
	v_exp_f32_e32 v147, v147
	v_exp_f32_e32 v163, v163
	v_max3_f32 v225, v225, v229, v175
	v_add_f32_e32 v148, v148, v180
	v_add_f32_e32 v164, v164, v198
	v_max_f32_e32 v217, v217, v221
	v_exp_f32_e32 v148, v148
	v_exp_f32_e32 v164, v164
	v_max_f32_e32 v219, v219, v225
	v_add_f32_e32 v149, v149, v180
	v_add_f32_e32 v165, v165, v198
	v_add_f32_e32 v221, v200, v217
	v_exp_f32_e32 v149, v149
	v_exp_f32_e32 v165, v165
	v_add_f32_e32 v225, v200, v219
	v_add_f32_e32 v150, v150, v180
	v_add_f32_e32 v166, v166, v198
	v_cmp_gt_f32_e32 vcc, v221, v227
	v_exp_f32_e32 v150, v150
	v_exp_f32_e32 v166, v166
	v_cmp_gt_f32_e64 s[0:1], v225, v215
	v_sub_f32_e32 v223, v221, v227
	v_sub_f32_e32 v229, v225, v215
	v_max_f32_e32 v223, v223, v229
	v_add_f32_e32 v223, 0x43280000, v223
	v_cmp_nlt_f32_e64 s[98:99], v223, 0
	v_add_f32_e32 v151, v151, v180
	v_add_f32_e32 v167, v167, v198
	v_exp_f32_e32 v151, v151
	v_exp_f32_e32 v167, v167
	v_add_f32_e32 v215, v144, v145
	v_add_f32_e32 v217, v160, v161
	v_add_f32_e32 v215, v215, v146
	v_add_f32_e32 v217, v217, v162
	v_add_f32_e32 v215, v215, v147
	v_add_f32_e32 v217, v217, v163
	v_add_f32_e32 v215, v215, v148
	v_add_f32_e32 v217, v217, v164
	v_add_f32_e32 v215, v215, v149
	v_add_f32_e32 v217, v217, v165
	v_add_f32_e32 v215, v215, v150
	v_add_f32_e32 v217, v217, v166
	v_add_f32_e32 v215, v215, v151
	v_add_f32_e32 v217, v217, v167
	v_cvt_pk_bf16_f32 v144, v144, v145
	v_cvt_pk_bf16_f32 v160, v160, v161
	v_cvt_pk_bf16_f32 v145, v146, v147
	v_cvt_pk_bf16_f32 v161, v162, v163
	v_cvt_pk_bf16_f32 v146, v148, v149
	v_cvt_pk_bf16_f32 v162, v164, v165
	v_cvt_pk_bf16_f32 v147, v150, v151
	v_cvt_pk_bf16_f32 v163, v166, v167
	ds_read_b64_tr_b16 v[148:149], v216 offset:4096
	ds_read_b64_tr_b16 v[150:151], v218 offset:4096
	ds_read_b64_tr_b16 v[164:165], v220 offset:4096
	ds_read_b64_tr_b16 v[166:167], v222 offset:4096
	s_or_b64 vcc, vcc, s[0:1]
	s_cbranch_vccnz .Lat2_redo
	s_cmp_eq_u64 s[98:99], 0
	s_cselect_b32 s51, 1, 0
	s_cbranch_scc1 .Lat2_skip
	s_waitcnt lgkmcnt(4)
	v_mfma_f32_32x32x16_bf16 v[112:127], v[202:205], v[144:147], v[112:127]
	v_add_f32_e32 v152, v152, v180
	v_add_f32_e32 v168, v168, v198
	v_exp_f32_e32 v152, v152
	v_exp_f32_e32 v168, v168
	v_mfma_f32_32x32x16_bf16 v[96:111], v[202:205], v[160:163], v[96:111]
	v_add_f32_e32 v153, v153, v180
	v_add_f32_e32 v169, v169, v198
	v_exp_f32_e32 v153, v153
	v_exp_f32_e32 v169, v169
	ds_read_b64_tr_b16 v[202:203], v224 offset:4096
	ds_read_b64_tr_b16 v[204:205], v226 offset:4096
	v_mfma_f32_32x32x16_bf16 v[64:79], v[244:247], v[144:147], v[64:79]
	v_add_f32_e32 v154, v154, v180
	v_add_f32_e32 v170, v170, v198
	v_exp_f32_e32 v154, v154
	v_exp_f32_e32 v170, v170
	v_mfma_f32_32x32x16_bf16 v[80:95], v[244:247], v[160:163], v[80:95]
	v_add_f32_e32 v155, v155, v180
	v_add_f32_e32 v171, v171, v198
	v_exp_f32_e32 v155, v155
	v_exp_f32_e32 v171, v171
	ds_read_b64_tr_b16 v[244:245], v228 offset:4096
	ds_read_b64_tr_b16 v[246:247], v230 offset:4096
	v_mfma_f32_32x32x16_bf16 v[32:47], v[248:251], v[144:147], v[32:47]
	v_add_f32_e32 v156, v156, v180
	v_add_f32_e32 v172, v172, v198
	v_exp_f32_e32 v156, v156
	v_exp_f32_e32 v172, v172
	v_mfma_f32_32x32x16_bf16 v[48:63], v[248:251], v[160:163], v[48:63]
	v_add_f32_e32 v157, v157, v180
	v_add_f32_e32 v173, v173, v198
	v_exp_f32_e32 v157, v157
	v_exp_f32_e32 v173, v173
	v_mfma_f32_32x32x16_bf16 v[0:15], v[252:255], v[144:147], v[0:15]
	v_add_f32_e32 v158, v158, v180
	v_add_f32_e32 v174, v174, v198
	v_exp_f32_e32 v158, v158
	v_exp_f32_e32 v174, v174
	v_mfma_f32_32x32x16_bf16 v[16:31], v[252:255], v[160:163], v[16:31]
	v_add_f32_e32 v159, v159, v180
	v_add_f32_e32 v175, v175, v198
	v_exp_f32_e32 v159, v159
	v_exp_f32_e32 v175, v175
	v_cvt_pk_bf16_f32 v248, v152, v153
	v_cvt_pk_bf16_f32 v252, v168, v169
	v_cvt_pk_bf16_f32 v249, v154, v155
	v_cvt_pk_bf16_f32 v253, v170, v171
	v_cvt_pk_bf16_f32 v250, v156, v157
	v_cvt_pk_bf16_f32 v254, v172, v173
	v_cvt_pk_bf16_f32 v251, v158, v159
	v_cvt_pk_bf16_f32 v255, v174, v175
	s_nop 0
	s_waitcnt lgkmcnt(6)
	v_mfma_f32_32x32x16_bf16 v[112:127], v[148:151], v[248:251], v[112:127]
	v_add_f32_e32 v215, v215, v152
	v_add_f32_e32 v217, v217, v168
	v_mfma_f32_32x32x16_bf16 v[96:111], v[148:151], v[252:255], v[96:111]
	v_add_f32_e32 v215, v215, v153
	v_add_f32_e32 v217, v217, v169
	v_add_f32_e32 v215, v215, v154
	s_waitcnt lgkmcnt(4)
	v_mfma_f32_32x32x16_bf16 v[64:79], v[164:167], v[248:251], v[64:79]
	v_add_f32_e32 v217, v217, v170
	v_add_f32_e32 v215, v215, v155
	v_mfma_f32_32x32x16_bf16 v[80:95], v[164:167], v[252:255], v[80:95]
	v_add_f32_e32 v217, v217, v171
	v_add_f32_e32 v215, v215, v156
	v_add_f32_e32 v217, v217, v172
	s_waitcnt lgkmcnt(2)
	v_mfma_f32_32x32x16_bf16 v[32:47], v[202:205], v[248:251], v[32:47]
	v_add_f32_e32 v215, v215, v157
	v_add_f32_e32 v217, v217, v173
	v_mfma_f32_32x32x16_bf16 v[48:63], v[202:205], v[252:255], v[48:63]
	v_add_f32_e32 v215, v215, v158
	v_add_f32_e32 v217, v217, v174
	v_add_f32_e32 v215, v215, v159
	s_waitcnt lgkmcnt(0)
	v_mfma_f32_32x32x16_bf16 v[0:15], v[244:247], v[248:251], v[0:15]
	v_add_f32_e32 v217, v217, v175
	v_add_f32_e32 v197, v197, v215
	v_mfma_f32_32x32x16_bf16 v[16:31], v[244:247], v[252:255], v[16:31]
	v_add_f32_e32 v196, v196, v217

.LBB0_787:
	s_cmp_lg_u32 s51, 0
	s_cbranch_scc1 .Lat3_probe
	ds_read_b128 v[160:163], v237 offset:24576
	ds_read_b128 v[164:167], v189
	ds_read_b128 v[202:205], v235 offset:24576
	ds_read_b128 v[244:247], v189 offset:4096
	ds_read_b128 v[248:251], v236 offset:24576
	ds_read_b128 v[252:255], v189 offset:1024
	s_cmp_lg_u32 s66, s40
	s_waitcnt lgkmcnt(4)
	v_mfma_f32_32x32x16_bf16 v[144:159], v[160:163], v[164:167], v[128:143]
	s_waitcnt lgkmcnt(2)
	v_mfma_f32_32x32x16_bf16 v[160:175], v[202:205], v[244:247], v[128:143]
	ds_read_b128 v[202:205], v234 offset:24576
	ds_read_b128 v[244:247], v189 offset:5120
	v_add_u32_e32 v215, s40, v185
	v_add_u32_e32 v215, 0xa0, v215
	v_cvt_f32_i32_e32 v215, v215
	v_add_f32_e32 v227, 0x41000000, v199
	v_mul_f32_e32 v200, v184, v215
	v_add_f32_e32 v215, 0x41000000, v201
	s_waitcnt lgkmcnt(2)
	v_mfma_f32_32x32x16_bf16 v[144:159], v[248:251], v[252:255], v[144:159]
	ds_read_b128 v[248:251], v241 offset:24576
	ds_read_b128 v[252:255], v189 offset:2048
	s_waitcnt lgkmcnt(2)
	v_mfma_f32_32x32x16_bf16 v[160:175], v[202:205], v[244:247], v[160:175]
	ds_read_b128 v[202:205], v239 offset:24576
	ds_read_b128 v[244:247], v189 offset:6144
	s_waitcnt lgkmcnt(2)
	v_mfma_f32_32x32x16_bf16 v[144:159], v[248:251], v[252:255], v[144:159]
	ds_read_b128 v[248:251], v240 offset:24576
	ds_read_b128 v[252:255], v189 offset:3072
	s_waitcnt lgkmcnt(2)
	v_mfma_f32_32x32x16_bf16 v[160:175], v[202:205], v[244:247], v[160:175]
	ds_read_b128 v[202:205], v238 offset:24576
	ds_read_b128 v[244:247], v189 offset:7168
	s_waitcnt lgkmcnt(2)
	v_mfma_f32_32x32x16_bf16 v[144:159], v[248:251], v[252:255], v[144:159]
	s_waitcnt lgkmcnt(0)
	v_mfma_f32_32x32x16_bf16 v[160:175], v[202:205], v[244:247], v[160:175]
	ds_read_b64_tr_b16 v[202:203], v216 offset:24576
	ds_read_b64_tr_b16 v[204:205], v218 offset:24576
	ds_read_b64_tr_b16 v[244:245], v220 offset:24576
	ds_read_b64_tr_b16 v[246:247], v222 offset:24576
	ds_read_b64_tr_b16 v[248:249], v224 offset:24576
	ds_read_b64_tr_b16 v[250:251], v226 offset:24576
	ds_read_b64_tr_b16 v[252:253], v228 offset:24576
	ds_read_b64_tr_b16 v[254:255], v230 offset:24576
	s_cbranch_scc0 .Lat3_diag
.Lat3_go:
	v_sub_f32_e32 v180, v200, v199
	v_sub_f32_e32 v198, v200, v201
	s_nop 0
	v_max3_f32 v217, v144, v145, v146
	v_max3_f32 v219, v160, v161, v162
	v_max3_f32 v221, v147, v148, v149
	v_max3_f32 v225, v163, v164, v165
	v_max3_f32 v223, v150, v151, v152
	v_max3_f32 v229, v166, v167, v168
	v_add_f32_e32 v144, v144, v180
	v_add_f32_e32 v160, v160, v198
	v_max3_f32 v217, v217, v221, v223
	v_exp_f32_e32 v144, v144
	v_exp_f32_e32 v160, v160
	v_max3_f32 v219, v219, v225, v229
	v_add_f32_e32 v145, v145, v180
	v_add_f32_e32 v161, v161, v198
	v_max3_f32 v221, v153, v154, v155
	v_exp_f32_e32 v145, v145
	v_exp_f32_e32 v161, v161
	v_max3_f32 v225, v169, v170, v171
	v_add_f32_e32 v146, v146, v180
	v_add_f32_e32 v162, v162, v198
	v_max3_f32 v223, v156, v157, v158
	v_exp_f32_e32 v146, v146
	v_exp_f32_e32 v162, v162
	v_max3_f32 v229, v172, v173, v174
	v_add_f32_e32 v147, v147, v180
	v_add_f32_e32 v163, v163, v198
	v_max3_f32 v221, v221, v223, v159
	v_exp_f32_e32 v147, v147
	v_exp_f32_e32 v163, v163
	v_max3_f32 v225, v225, v229, v175
	v_add_f32_e32 v148, v148, v180
	v_add_f32_e32 v164, v164, v198
	v_max_f32_e32 v217, v217, v221
	v_exp_f32_e32 v148, v148
	v_exp_f32_e32 v164, v164
	v_max_f32_e32 v219, v219, v225
	v_add_f32_e32 v149, v149, v180
	v_add_f32_e32 v165, v165, v198
	v_add_f32_e32 v221, v200, v217
	v_exp_f32_e32 v149, v149
	v_exp_f32_e32 v165, v165
	v_add_f32_e32 v225, v200, v219
	v_add_f32_e32 v150, v150, v180
	v_add_f32_e32 v166, v166, v198
	v_cmp_gt_f32_e32 vcc, v221, v227
	v_exp_f32_e32 v150, v150
	v_exp_f32_e32 v166, v166
	v_cmp_gt_f32_e64 s[0:1], v225, v215
	v_sub_f32_e32 v223, v221, v227
	v_sub_f32_e32 v229, v225, v215
	v_max_f32_e32 v223, v223, v229
	v_add_f32_e32 v223, 0x43280000, v223
	v_cmp_nlt_f32_e64 s[98:99], v223, 0
	v_add_f32_e32 v151, v151, v180
	v_add_f32_e32 v167, v167, v198
	v_exp_f32_e32 v151, v151
	v_exp_f32_e32 v167, v167
	v_add_f32_e32 v215, v144, v145
	v_add_f32_e32 v217, v160, v161
	v_add_f32_e32 v215, v215, v146
	v_add_f32_e32 v217, v217, v162
	v_add_f32_e32 v215, v215, v147
	v_add_f32_e32 v217, v217, v163
	v_add_f32_e32 v215, v215, v148
	v_add_f32_e32 v217, v217, v164
	v_add_f32_e32 v215, v215, v149
	v_add_f32_e32 v217, v217, v165
	v_add_f32_e32 v215, v215, v150
	v_add_f32_e32 v217, v217, v166
	v_add_f32_e32 v215, v215, v151
	v_add_f32_e32 v217, v217, v167
	v_cvt_pk_bf16_f32 v144, v144, v145
	v_cvt_pk_bf16_f32 v160, v160, v161
	v_cvt_pk_bf16_f32 v145, v146, v147
	v_cvt_pk_bf16_f32 v161, v162, v163
	v_cvt_pk_bf16_f32 v146, v148, v149
	v_cvt_pk_bf16_f32 v162, v164, v165
	v_cvt_pk_bf16_f32 v147, v150, v151
	v_cvt_pk_bf16_f32 v163, v166, v167
	ds_read_b64_tr_b16 v[148:149], v216 offset:28672
	ds_read_b64_tr_b16 v[150:151], v218 offset:28672
	ds_read_b64_tr_b16 v[164:165], v220 offset:28672
	ds_read_b64_tr_b16 v[166:167], v222 offset:28672
	s_or_b64 vcc, vcc, s[0:1]
	s_cbranch_vccnz .Lat3_redo
	s_cmp_eq_u64 s[98:99], 0
	s_cselect_b32 s51, 1, 0
	s_cbranch_scc1 .Lat3_skip
	s_waitcnt lgkmcnt(4)
	v_mfma_f32_32x32x16_bf16 v[112:127], v[202:205], v[144:147], v[112:127]
	v_add_f32_e32 v152, v152, v180
	v_add_f32_e32 v168, v168, v198
	v_exp_f32_e32 v152, v152
	v_exp_f32_e32 v168, v168
	v_mfma_f32_32x32x16_bf16 v[96:111], v[202:205], v[160:163], v[96:111]
	v_add_f32_e32 v153, v153, v180
	v_add_f32_e32 v169, v169, v198
	v_exp_f32_e32 v153, v153
	v_exp_f32_e32 v169, v169
	ds_read_b64_tr_b16 v[202:203], v224 offset:28672
	ds_read_b64_tr_b16 v[204:205], v226 offset:28672
	v_mfma_f32_32x32x16_bf16 v[64:79], v[244:247], v[144:147], v[64:79]
	v_add_f32_e32 v154, v154, v180
	v_add_f32_e32 v170, v170, v198
	v_exp_f32_e32 v154, v154
	v_exp_f32_e32 v170, v170
	v_mfma_f32_32x32x16_bf16 v[80:95], v[244:247], v[160:163], v[80:95]
	v_add_f32_e32 v155, v155, v180
	v_add_f32_e32 v171, v171, v198
	v_exp_f32_e32 v155, v155
	v_exp_f32_e32 v171, v171
	ds_read_b64_tr_b16 v[244:245], v228 offset:28672
	ds_read_b64_tr_b16 v[246:247], v230 offset:28672
	v_mfma_f32_32x32x16_bf16 v[32:47], v[248:251], v[144:147], v[32:47]
	v_add_f32_e32 v156, v156, v180
	v_add_f32_e32 v172, v172, v198
	v_exp_f32_e32 v156, v156
	v_exp_f32_e32 v172, v172
	v_mfma_f32_32x32x16_bf16 v[48:63], v[248:251], v[160:163], v[48:63]
	v_add_f32_e32 v157, v157, v180
	v_add_f32_e32 v173, v173, v198
	v_exp_f32_e32 v157, v157
	v_exp_f32_e32 v173, v173
	v_mfma_f32_32x32x16_bf16 v[0:15], v[252:255], v[144:147], v[0:15]
	v_add_f32_e32 v158, v158, v180
	v_add_f32_e32 v174, v174, v198
	v_exp_f32_e32 v158, v158
	v_exp_f32_e32 v174, v174
	v_mfma_f32_32x32x16_bf16 v[16:31], v[252:255], v[160:163], v[16:31]
	v_add_f32_e32 v159, v159, v180
	v_add_f32_e32 v175, v175, v198
	v_exp_f32_e32 v159, v159
	v_exp_f32_e32 v175, v175
	v_cvt_pk_bf16_f32 v248, v152, v153
	v_cvt_pk_bf16_f32 v252, v168, v169
	v_cvt_pk_bf16_f32 v249, v154, v155
	v_cvt_pk_bf16_f32 v253, v170, v171
	v_cvt_pk_bf16_f32 v250, v156, v157
	v_cvt_pk_bf16_f32 v254, v172, v173
	v_cvt_pk_bf16_f32 v251, v158, v159
	v_cvt_pk_bf16_f32 v255, v174, v175
	s_nop 0
	s_waitcnt lgkmcnt(6)
	v_mfma_f32_32x32x16_bf16 v[112:127], v[148:151], v[248:251], v[112:127]
	v_add_f32_e32 v215, v215, v152
	v_add_f32_e32 v217, v217, v168
	v_mfma_f32_32x32x16_bf16 v[96:111], v[148:151], v[252:255], v[96:111]
	v_add_f32_e32 v215, v215, v153
	v_add_f32_e32 v217, v217, v169
	v_add_f32_e32 v215, v215, v154
	s_waitcnt lgkmcnt(4)
	v_mfma_f32_32x32x16_bf16 v[64:79], v[164:167], v[248:251], v[64:79]
	v_add_f32_e32 v217, v217, v170
	v_add_f32_e32 v215, v215, v155
	v_mfma_f32_32x32x16_bf16 v[80:95], v[164:167], v[252:255], v[80:95]
	v_add_f32_e32 v217, v217, v171
	v_add_f32_e32 v215, v215, v156
	v_add_f32_e32 v217, v217, v172
	s_waitcnt lgkmcnt(2)
	v_mfma_f32_32x32x16_bf16 v[32:47], v[202:205], v[248:251], v[32:47]
	v_add_f32_e32 v215, v215, v157
	v_add_f32_e32 v217, v217, v173
	v_mfma_f32_32x32x16_bf16 v[48:63], v[202:205], v[252:255], v[48:63]
	v_add_f32_e32 v215, v215, v158
	v_add_f32_e32 v217, v217, v174
	v_add_f32_e32 v215, v215, v159
	s_waitcnt lgkmcnt(0)
	v_mfma_f32_32x32x16_bf16 v[0:15], v[244:247], v[248:251], v[0:15]
	v_add_f32_e32 v217, v217, v175
	v_add_f32_e32 v197, v197, v215
	v_mfma_f32_32x32x16_bf16 v[16:31], v[244:247], v[252:255], v[16:31]
	v_add_f32_e32 v196, v196, v217

.LBB0_792:
	s_cmp_lg_u32 s51, 0
	s_cbranch_scc1 .Lat4_probe
	ds_read_b128 v[160:163], v237 offset:16384
	ds_read_b128 v[164:167], v189
	ds_read_b128 v[202:205], v235 offset:16384
	ds_read_b128 v[244:247], v189 offset:4096
	ds_read_b128 v[248:251], v236 offset:16384
	ds_read_b128 v[252:255], v189 offset:1024
	s_cmp_lg_u32 s39, s40
	s_waitcnt lgkmcnt(4)
	v_mfma_f32_32x32x16_bf16 v[144:159], v[160:163], v[164:167], v[128:143]
	s_waitcnt lgkmcnt(2)
	v_mfma_f32_32x32x16_bf16 v[160:175], v[202:205], v[244:247], v[128:143]
	ds_read_b128 v[202:205], v234 offset:16384
	ds_read_b128 v[244:247], v189 offset:5120
	v_add_u32_e32 v215, s40, v185
	v_add_u32_e32 v215, 0x80, v215
	v_cvt_f32_i32_e32 v215, v215
	v_add_f32_e32 v227, 0x41000000, v199
	v_mul_f32_e32 v200, v184, v215
	v_add_f32_e32 v215, 0x41000000, v201
	s_waitcnt lgkmcnt(2)
	v_mfma_f32_32x32x16_bf16 v[144:159], v[248:251], v[252:255], v[144:159]
	ds_read_b128 v[248:251], v241 offset:16384
	ds_read_b128 v[252:255], v189 offset:2048
	s_waitcnt lgkmcnt(2)
	v_mfma_f32_32x32x16_bf16 v[160:175], v[202:205], v[244:247], v[160:175]
	ds_read_b128 v[202:205], v239 offset:16384
	ds_read_b128 v[244:247], v189 offset:6144
	s_waitcnt lgkmcnt(2)
	v_mfma_f32_32x32x16_bf16 v[144:159], v[248:251], v[252:255], v[144:159]
	ds_read_b128 v[248:251], v240 offset:16384
	ds_read_b128 v[252:255], v189 offset:3072
	s_waitcnt lgkmcnt(2)
	v_mfma_f32_32x32x16_bf16 v[160:175], v[202:205], v[244:247], v[160:175]
	ds_read_b128 v[202:205], v238 offset:16384
	ds_read_b128 v[244:247], v189 offset:7168
	s_waitcnt lgkmcnt(2)
	v_mfma_f32_32x32x16_bf16 v[144:159], v[248:251], v[252:255], v[144:159]
	s_waitcnt lgkmcnt(0)
	v_mfma_f32_32x32x16_bf16 v[160:175], v[202:205], v[244:247], v[160:175]
	ds_read_b64_tr_b16 v[202:203], v216 offset:16384
	ds_read_b64_tr_b16 v[204:205], v218 offset:16384
	ds_read_b64_tr_b16 v[244:245], v220 offset:16384
	ds_read_b64_tr_b16 v[246:247], v222 offset:16384
	ds_read_b64_tr_b16 v[248:249], v224 offset:16384
	ds_read_b64_tr_b16 v[250:251], v226 offset:16384
	ds_read_b64_tr_b16 v[252:253], v228 offset:16384
	ds_read_b64_tr_b16 v[254:255], v230 offset:16384
	s_cbranch_scc0 .Lat4_diag
.Lat4_go:
	v_sub_f32_e32 v180, v200, v199
	v_sub_f32_e32 v198, v200, v201
	s_nop 0
	v_max3_f32 v217, v144, v145, v146
	v_max3_f32 v219, v160, v161, v162
	v_max3_f32 v221, v147, v148, v149
	v_max3_f32 v225, v163, v164, v165
	v_max3_f32 v223, v150, v151, v152
	v_max3_f32 v229, v166, v167, v168
	v_add_f32_e32 v144, v144, v180
	v_add_f32_e32 v160, v160, v198
	v_max3_f32 v217, v217, v221, v223
	v_exp_f32_e32 v144, v144
	v_exp_f32_e32 v160, v160
	v_max3_f32 v219, v219, v225, v229
	v_add_f32_e32 v145, v145, v180
	v_add_f32_e32 v161, v161, v198
	v_max3_f32 v221, v153, v154, v155
	v_exp_f32_e32 v145, v145
	v_exp_f32_e32 v161, v161
	v_max3_f32 v225, v169, v170, v171
	v_add_f32_e32 v146, v146, v180
	v_add_f32_e32 v162, v162, v198
	v_max3_f32 v223, v156, v157, v158
	v_exp_f32_e32 v146, v146
	v_exp_f32_e32 v162, v162
	v_max3_f32 v229, v172, v173, v174
	v_add_f32_e32 v147, v147, v180
	v_add_f32_e32 v163, v163, v198
	v_max3_f32 v221, v221, v223, v159
	v_exp_f32_e32 v147, v147
	v_exp_f32_e32 v163, v163
	v_max3_f32 v225, v225, v229, v175
	v_add_f32_e32 v148, v148, v180
	v_add_f32_e32 v164, v164, v198
	v_max_f32_e32 v217, v217, v221
	v_exp_f32_e32 v148, v148
	v_exp_f32_e32 v164, v164
	v_max_f32_e32 v219, v219, v225
	v_add_f32_e32 v149, v149, v180
	v_add_f32_e32 v165, v165, v198
	v_add_f32_e32 v221, v200, v217
	v_exp_f32_e32 v149, v149
	v_exp_f32_e32 v165, v165
	v_add_f32_e32 v225, v200, v219
	v_add_f32_e32 v150, v150, v180
	v_add_f32_e32 v166, v166, v198
	v_cmp_gt_f32_e32 vcc, v221, v227
	v_exp_f32_e32 v150, v150
	v_exp_f32_e32 v166, v166
	v_cmp_gt_f32_e64 s[0:1], v225, v215
	v_sub_f32_e32 v223, v221, v227
	v_sub_f32_e32 v229, v225, v215
	v_max_f32_e32 v223, v223, v229
	v_add_f32_e32 v223, 0x43280000, v223
	v_cmp_nlt_f32_e64 s[98:99], v223, 0
	v_add_f32_e32 v151, v151, v180
	v_add_f32_e32 v167, v167, v198
	v_exp_f32_e32 v151, v151
	v_exp_f32_e32 v167, v167
	v_add_f32_e32 v215, v144, v145
	v_add_f32_e32 v217, v160, v161
	v_add_f32_e32 v215, v215, v146
	v_add_f32_e32 v217, v217, v162
	v_add_f32_e32 v215, v215, v147
	v_add_f32_e32 v217, v217, v163
	v_add_f32_e32 v215, v215, v148
	v_add_f32_e32 v217, v217, v164
	v_add_f32_e32 v215, v215, v149
	v_add_f32_e32 v217, v217, v165
	v_add_f32_e32 v215, v215, v150
	v_add_f32_e32 v217, v217, v166
	v_add_f32_e32 v215, v215, v151
	v_add_f32_e32 v217, v217, v167
	v_cvt_pk_bf16_f32 v144, v144, v145
	v_cvt_pk_bf16_f32 v160, v160, v161
	v_cvt_pk_bf16_f32 v145, v146, v147
	v_cvt_pk_bf16_f32 v161, v162, v163
	v_cvt_pk_bf16_f32 v146, v148, v149
	v_cvt_pk_bf16_f32 v162, v164, v165
	v_cvt_pk_bf16_f32 v147, v150, v151
	v_cvt_pk_bf16_f32 v163, v166, v167
	ds_read_b64_tr_b16 v[148:149], v216 offset:20480
	ds_read_b64_tr_b16 v[150:151], v218 offset:20480
	ds_read_b64_tr_b16 v[164:165], v220 offset:20480
	ds_read_b64_tr_b16 v[166:167], v222 offset:20480
	s_or_b64 vcc, vcc, s[0:1]
	s_cbranch_vccnz .Lat4_redo
	s_cmp_eq_u64 s[98:99], 0
	s_cselect_b32 s51, 1, 0
	s_cbranch_scc1 .Lat4_skip
	s_waitcnt lgkmcnt(4)
	v_mfma_f32_32x32x16_bf16 v[112:127], v[202:205], v[144:147], v[112:127]
	v_add_f32_e32 v152, v152, v180
	v_add_f32_e32 v168, v168, v198
	v_exp_f32_e32 v152, v152
	v_exp_f32_e32 v168, v168
	v_mfma_f32_32x32x16_bf16 v[96:111], v[202:205], v[160:163], v[96:111]
	v_add_f32_e32 v153, v153, v180
	v_add_f32_e32 v169, v169, v198
	v_exp_f32_e32 v153, v153
	v_exp_f32_e32 v169, v169
	ds_read_b64_tr_b16 v[202:203], v224 offset:20480
	ds_read_b64_tr_b16 v[204:205], v226 offset:20480
	v_mfma_f32_32x32x16_bf16 v[64:79], v[244:247], v[144:147], v[64:79]
	v_add_f32_e32 v154, v154, v180
	v_add_f32_e32 v170, v170, v198
	v_exp_f32_e32 v154, v154
	v_exp_f32_e32 v170, v170
	v_mfma_f32_32x32x16_bf16 v[80:95], v[244:247], v[160:163], v[80:95]
	v_add_f32_e32 v155, v155, v180
	v_add_f32_e32 v171, v171, v198
	v_exp_f32_e32 v155, v155
	v_exp_f32_e32 v171, v171
	ds_read_b64_tr_b16 v[244:245], v228 offset:20480
	ds_read_b64_tr_b16 v[246:247], v230 offset:20480
	v_mfma_f32_32x32x16_bf16 v[32:47], v[248:251], v[144:147], v[32:47]
	v_add_f32_e32 v156, v156, v180
	v_add_f32_e32 v172, v172, v198
	v_exp_f32_e32 v156, v156
	v_exp_f32_e32 v172, v172
	v_mfma_f32_32x32x16_bf16 v[48:63], v[248:251], v[160:163], v[48:63]
	v_add_f32_e32 v157, v157, v180
	v_add_f32_e32 v173, v173, v198
	v_exp_f32_e32 v157, v157
	v_exp_f32_e32 v173, v173
	v_mfma_f32_32x32x16_bf16 v[0:15], v[252:255], v[144:147], v[0:15]
	v_add_f32_e32 v158, v158, v180
	v_add_f32_e32 v174, v174, v198
	v_exp_f32_e32 v158, v158
	v_exp_f32_e32 v174, v174
	v_mfma_f32_32x32x16_bf16 v[16:31], v[252:255], v[160:163], v[16:31]
	v_add_f32_e32 v159, v159, v180
	v_add_f32_e32 v175, v175, v198
	v_exp_f32_e32 v159, v159
	v_exp_f32_e32 v175, v175
	v_cvt_pk_bf16_f32 v248, v152, v153
	v_cvt_pk_bf16_f32 v252, v168, v169
	v_cvt_pk_bf16_f32 v249, v154, v155
	v_cvt_pk_bf16_f32 v253, v170, v171
	v_cvt_pk_bf16_f32 v250, v156, v157
	v_cvt_pk_bf16_f32 v254, v172, v173
	v_cvt_pk_bf16_f32 v251, v158, v159
	v_cvt_pk_bf16_f32 v255, v174, v175
	s_nop 0
	s_waitcnt lgkmcnt(6)
	v_mfma_f32_32x32x16_bf16 v[112:127], v[148:151], v[248:251], v[112:127]
	v_add_f32_e32 v215, v215, v152
	v_add_f32_e32 v217, v217, v168
	v_mfma_f32_32x32x16_bf16 v[96:111], v[148:151], v[252:255], v[96:111]
	v_add_f32_e32 v215, v215, v153
	v_add_f32_e32 v217, v217, v169
	v_add_f32_e32 v215, v215, v154
	s_waitcnt lgkmcnt(4)
	v_mfma_f32_32x32x16_bf16 v[64:79], v[164:167], v[248:251], v[64:79]
	v_add_f32_e32 v217, v217, v170
	v_add_f32_e32 v215, v215, v155
	v_mfma_f32_32x32x16_bf16 v[80:95], v[164:167], v[252:255], v[80:95]
	v_add_f32_e32 v217, v217, v171
	v_add_f32_e32 v215, v215, v156
	v_add_f32_e32 v217, v217, v172
	s_waitcnt lgkmcnt(2)
	v_mfma_f32_32x32x16_bf16 v[32:47], v[202:205], v[248:251], v[32:47]
	v_add_f32_e32 v215, v215, v157
	v_add_f32_e32 v217, v217, v173
	v_mfma_f32_32x32x16_bf16 v[48:63], v[202:205], v[252:255], v[48:63]
	v_add_f32_e32 v215, v215, v158
	v_add_f32_e32 v217, v217, v174
	v_add_f32_e32 v215, v215, v159
	s_waitcnt lgkmcnt(0)
	v_mfma_f32_32x32x16_bf16 v[0:15], v[244:247], v[248:251], v[0:15]
	v_add_f32_e32 v217, v217, v175
	v_add_f32_e32 v197, v197, v215
	v_mfma_f32_32x32x16_bf16 v[16:31], v[244:247], v[252:255], v[16:31]
	v_add_f32_e32 v196, v196, v217

.LBB0_800:
	s_cmp_lg_u32 s51, 0
	s_cbranch_scc1 .Lat5_probe
	ds_read_b128 v[160:163], v237 offset:40960
	ds_read_b128 v[164:167], v189
	ds_read_b128 v[202:205], v235 offset:40960
	ds_read_b128 v[244:247], v189 offset:4096
	ds_read_b128 v[248:251], v236 offset:40960
	ds_read_b128 v[252:255], v189 offset:1024
	s_cmp_lg_u32 s65, s40
	s_waitcnt lgkmcnt(4)
	v_mfma_f32_32x32x16_bf16 v[144:159], v[160:163], v[164:167], v[128:143]
	s_waitcnt lgkmcnt(2)
	v_mfma_f32_32x32x16_bf16 v[160:175], v[202:205], v[244:247], v[128:143]
	ds_read_b128 v[202:205], v234 offset:40960
	ds_read_b128 v[244:247], v189 offset:5120
	v_add_u32_e32 v215, s40, v185
	v_add_u32_e32 v215, 0x60, v215
	v_cvt_f32_i32_e32 v215, v215
	v_add_f32_e32 v227, 0x41000000, v199
	v_mul_f32_e32 v200, v184, v215
	v_add_f32_e32 v215, 0x41000000, v201
	s_waitcnt lgkmcnt(2)
	v_mfma_f32_32x32x16_bf16 v[144:159], v[248:251], v[252:255], v[144:159]
	ds_read_b128 v[248:251], v241 offset:40960
	ds_read_b128 v[252:255], v189 offset:2048
	s_waitcnt lgkmcnt(2)
	v_mfma_f32_32x32x16_bf16 v[160:175], v[202:205], v[244:247], v[160:175]
	ds_read_b128 v[202:205], v239 offset:40960
	ds_read_b128 v[244:247], v189 offset:6144
	s_waitcnt lgkmcnt(2)
	v_mfma_f32_32x32x16_bf16 v[144:159], v[248:251], v[252:255], v[144:159]
	ds_read_b128 v[248:251], v240 offset:40960
	ds_read_b128 v[252:255], v189 offset:3072
	s_waitcnt lgkmcnt(2)
	v_mfma_f32_32x32x16_bf16 v[160:175], v[202:205], v[244:247], v[160:175]
	ds_read_b128 v[202:205], v238 offset:40960
	ds_read_b128 v[244:247], v189 offset:7168
	s_waitcnt lgkmcnt(2)
	v_mfma_f32_32x32x16_bf16 v[144:159], v[248:251], v[252:255], v[144:159]
	s_waitcnt lgkmcnt(0)
	v_mfma_f32_32x32x16_bf16 v[160:175], v[202:205], v[244:247], v[160:175]
	ds_read_b64_tr_b16 v[202:203], v216 offset:40960
	ds_read_b64_tr_b16 v[204:205], v218 offset:40960
	ds_read_b64_tr_b16 v[244:245], v220 offset:40960
	ds_read_b64_tr_b16 v[246:247], v222 offset:40960
	ds_read_b64_tr_b16 v[248:249], v224 offset:40960
	ds_read_b64_tr_b16 v[250:251], v226 offset:40960
	ds_read_b64_tr_b16 v[252:253], v228 offset:40960
	ds_read_b64_tr_b16 v[254:255], v230 offset:40960
	s_cbranch_scc0 .Lat5_diag
.Lat5_go:
	v_sub_f32_e32 v180, v200, v199
	v_sub_f32_e32 v198, v200, v201
	s_nop 0
	v_max3_f32 v217, v144, v145, v146
	v_max3_f32 v219, v160, v161, v162
	v_max3_f32 v221, v147, v148, v149
	v_max3_f32 v225, v163, v164, v165
	v_max3_f32 v223, v150, v151, v152
	v_max3_f32 v229, v166, v167, v168
	v_add_f32_e32 v144, v144, v180
	v_add_f32_e32 v160, v160, v198
	v_max3_f32 v217, v217, v221, v223
	v_exp_f32_e32 v144, v144
	v_exp_f32_e32 v160, v160
	v_max3_f32 v219, v219, v225, v229
	v_add_f32_e32 v145, v145, v180
	v_add_f32_e32 v161, v161, v198
	v_max3_f32 v221, v153, v154, v155
	v_exp_f32_e32 v145, v145
	v_exp_f32_e32 v161, v161
	v_max3_f32 v225, v169, v170, v171
	v_add_f32_e32 v146, v146, v180
	v_add_f32_e32 v162, v162, v198
	v_max3_f32 v223, v156, v157, v158
	v_exp_f32_e32 v146, v146
	v_exp_f32_e32 v162, v162
	v_max3_f32 v229, v172, v173, v174
	v_add_f32_e32 v147, v147, v180
	v_add_f32_e32 v163, v163, v198
	v_max3_f32 v221, v221, v223, v159
	v_exp_f32_e32 v147, v147
	v_exp_f32_e32 v163, v163
	v_max3_f32 v225, v225, v229, v175
	v_add_f32_e32 v148, v148, v180
	v_add_f32_e32 v164, v164, v198
	v_max_f32_e32 v217, v217, v221
	v_exp_f32_e32 v148, v148
	v_exp_f32_e32 v164, v164
	v_max_f32_e32 v219, v219, v225
	v_add_f32_e32 v149, v149, v180
	v_add_f32_e32 v165, v165, v198
	v_add_f32_e32 v221, v200, v217
	v_exp_f32_e32 v149, v149
	v_exp_f32_e32 v165, v165
	v_add_f32_e32 v225, v200, v219
	v_add_f32_e32 v150, v150, v180
	v_add_f32_e32 v166, v166, v198
	v_cmp_gt_f32_e32 vcc, v221, v227
	v_exp_f32_e32 v150, v150
	v_exp_f32_e32 v166, v166
	v_cmp_gt_f32_e64 s[0:1], v225, v215
	v_sub_f32_e32 v223, v221, v227
	v_sub_f32_e32 v229, v225, v215
	v_max_f32_e32 v223, v223, v229
	v_add_f32_e32 v223, 0x43280000, v223
	v_cmp_nlt_f32_e64 s[98:99], v223, 0
	v_add_f32_e32 v151, v151, v180
	v_add_f32_e32 v167, v167, v198
	v_exp_f32_e32 v151, v151
	v_exp_f32_e32 v167, v167
	v_add_f32_e32 v215, v144, v145
	v_add_f32_e32 v217, v160, v161
	v_add_f32_e32 v215, v215, v146
	v_add_f32_e32 v217, v217, v162
	v_add_f32_e32 v215, v215, v147
	v_add_f32_e32 v217, v217, v163
	v_add_f32_e32 v215, v215, v148
	v_add_f32_e32 v217, v217, v164
	v_add_f32_e32 v215, v215, v149
	v_add_f32_e32 v217, v217, v165
	v_add_f32_e32 v215, v215, v150
	v_add_f32_e32 v217, v217, v166
	v_add_f32_e32 v215, v215, v151
	v_add_f32_e32 v217, v217, v167
	v_cvt_pk_bf16_f32 v144, v144, v145
	v_cvt_pk_bf16_f32 v160, v160, v161
	v_cvt_pk_bf16_f32 v145, v146, v147
	v_cvt_pk_bf16_f32 v161, v162, v163
	v_cvt_pk_bf16_f32 v146, v148, v149
	v_cvt_pk_bf16_f32 v162, v164, v165
	v_cvt_pk_bf16_f32 v147, v150, v151
	v_cvt_pk_bf16_f32 v163, v166, v167
	ds_read_b64_tr_b16 v[148:149], v216 offset:45056
	ds_read_b64_tr_b16 v[150:151], v218 offset:45056
	ds_read_b64_tr_b16 v[164:165], v220 offset:45056
	ds_read_b64_tr_b16 v[166:167], v222 offset:45056
	s_or_b64 vcc, vcc, s[0:1]
	s_cbranch_vccnz .Lat5_redo
	s_cmp_eq_u64 s[98:99], 0
	s_cselect_b32 s51, 1, 0
	s_cbranch_scc1 .Lat5_skip
	s_waitcnt lgkmcnt(4)
	v_mfma_f32_32x32x16_bf16 v[112:127], v[202:205], v[144:147], v[112:127]
	v_add_f32_e32 v152, v152, v180
	v_add_f32_e32 v168, v168, v198
	v_exp_f32_e32 v152, v152
	v_exp_f32_e32 v168, v168
	v_mfma_f32_32x32x16_bf16 v[96:111], v[202:205], v[160:163], v[96:111]
	v_add_f32_e32 v153, v153, v180
	v_add_f32_e32 v169, v169, v198
	v_exp_f32_e32 v153, v153
	v_exp_f32_e32 v169, v169
	ds_read_b64_tr_b16 v[202:203], v224 offset:45056
	ds_read_b64_tr_b16 v[204:205], v226 offset:45056
	v_mfma_f32_32x32x16_bf16 v[64:79], v[244:247], v[144:147], v[64:79]
	v_add_f32_e32 v154, v154, v180
	v_add_f32_e32 v170, v170, v198
	v_exp_f32_e32 v154, v154
	v_exp_f32_e32 v170, v170
	v_mfma_f32_32x32x16_bf16 v[80:95], v[244:247], v[160:163], v[80:95]
	v_add_f32_e32 v155, v155, v180
	v_add_f32_e32 v171, v171, v198
	v_exp_f32_e32 v155, v155
	v_exp_f32_e32 v171, v171
	ds_read_b64_tr_b16 v[244:245], v228 offset:45056
	ds_read_b64_tr_b16 v[246:247], v230 offset:45056
	v_mfma_f32_32x32x16_bf16 v[32:47], v[248:251], v[144:147], v[32:47]
	v_add_f32_e32 v156, v156, v180
	v_add_f32_e32 v172, v172, v198
	v_exp_f32_e32 v156, v156
	v_exp_f32_e32 v172, v172
	v_mfma_f32_32x32x16_bf16 v[48:63], v[248:251], v[160:163], v[48:63]
	v_add_f32_e32 v157, v157, v180
	v_add_f32_e32 v173, v173, v198
	v_exp_f32_e32 v157, v157
	v_exp_f32_e32 v173, v173
	v_mfma_f32_32x32x16_bf16 v[0:15], v[252:255], v[144:147], v[0:15]
	v_add_f32_e32 v158, v158, v180
	v_add_f32_e32 v174, v174, v198
	v_exp_f32_e32 v158, v158
	v_exp_f32_e32 v174, v174
	v_mfma_f32_32x32x16_bf16 v[16:31], v[252:255], v[160:163], v[16:31]
	v_add_f32_e32 v159, v159, v180
	v_add_f32_e32 v175, v175, v198
	v_exp_f32_e32 v159, v159
	v_exp_f32_e32 v175, v175
	v_cvt_pk_bf16_f32 v248, v152, v153
	v_cvt_pk_bf16_f32 v252, v168, v169
	v_cvt_pk_bf16_f32 v249, v154, v155
	v_cvt_pk_bf16_f32 v253, v170, v171
	v_cvt_pk_bf16_f32 v250, v156, v157
	v_cvt_pk_bf16_f32 v254, v172, v173
	v_cvt_pk_bf16_f32 v251, v158, v159
	v_cvt_pk_bf16_f32 v255, v174, v175
	s_nop 0
	s_waitcnt lgkmcnt(6)
	v_mfma_f32_32x32x16_bf16 v[112:127], v[148:151], v[248:251], v[112:127]
	v_add_f32_e32 v215, v215, v152
	v_add_f32_e32 v217, v217, v168
	v_mfma_f32_32x32x16_bf16 v[96:111], v[148:151], v[252:255], v[96:111]
	v_add_f32_e32 v215, v215, v153
	v_add_f32_e32 v217, v217, v169
	v_add_f32_e32 v215, v215, v154
	s_waitcnt lgkmcnt(4)
	v_mfma_f32_32x32x16_bf16 v[64:79], v[164:167], v[248:251], v[64:79]
	v_add_f32_e32 v217, v217, v170
	v_add_f32_e32 v215, v215, v155
	v_mfma_f32_32x32x16_bf16 v[80:95], v[164:167], v[252:255], v[80:95]
	v_add_f32_e32 v217, v217, v171
	v_add_f32_e32 v215, v215, v156
	v_add_f32_e32 v217, v217, v172
	s_waitcnt lgkmcnt(2)
	v_mfma_f32_32x32x16_bf16 v[32:47], v[202:205], v[248:251], v[32:47]
	v_add_f32_e32 v215, v215, v157
	v_add_f32_e32 v217, v217, v173
	v_mfma_f32_32x32x16_bf16 v[48:63], v[202:205], v[252:255], v[48:63]
	v_add_f32_e32 v215, v215, v158
	v_add_f32_e32 v217, v217, v174
	v_add_f32_e32 v215, v215, v159
	s_waitcnt lgkmcnt(0)
	v_mfma_f32_32x32x16_bf16 v[0:15], v[244:247], v[248:251], v[0:15]
	v_add_f32_e32 v217, v217, v175
	v_add_f32_e32 v197, v197, v215
	v_mfma_f32_32x32x16_bf16 v[16:31], v[244:247], v[252:255], v[16:31]
	v_add_f32_e32 v196, v196, v217

.LBB0_805:
	s_cmp_lg_u32 s51, 0
	s_cbranch_scc1 .Lat6_probe
	ds_read_b128 v[160:163], v237 offset:32768
	ds_read_b128 v[164:167], v189
	ds_read_b128 v[202:205], v235 offset:32768
	ds_read_b128 v[244:247], v189 offset:4096
	ds_read_b128 v[248:251], v236 offset:32768
	ds_read_b128 v[252:255], v189 offset:1024
	s_cmp_lg_u32 s97, s40
	s_waitcnt lgkmcnt(4)
	v_mfma_f32_32x32x16_bf16 v[144:159], v[160:163], v[164:167], v[128:143]
	s_waitcnt lgkmcnt(2)
	v_mfma_f32_32x32x16_bf16 v[160:175], v[202:205], v[244:247], v[128:143]
	ds_read_b128 v[202:205], v234 offset:32768
	ds_read_b128 v[244:247], v189 offset:5120
	v_add_u32_e32 v215, s40, v185
	v_add_u32_e32 v215, 0x40, v215
	v_cvt_f32_i32_e32 v215, v215
	v_add_f32_e32 v227, 0x41000000, v199
	v_mul_f32_e32 v200, v184, v215
	v_add_f32_e32 v215, 0x41000000, v201
	s_waitcnt lgkmcnt(2)
	v_mfma_f32_32x32x16_bf16 v[144:159], v[248:251], v[252:255], v[144:159]
	ds_read_b128 v[248:251], v241 offset:32768
	ds_read_b128 v[252:255], v189 offset:2048
	s_waitcnt lgkmcnt(2)
	v_mfma_f32_32x32x16_bf16 v[160:175], v[202:205], v[244:247], v[160:175]
	ds_read_b128 v[202:205], v239 offset:32768
	ds_read_b128 v[244:247], v189 offset:6144
	s_waitcnt lgkmcnt(2)
	v_mfma_f32_32x32x16_bf16 v[144:159], v[248:251], v[252:255], v[144:159]
	ds_read_b128 v[248:251], v240 offset:32768
	ds_read_b128 v[252:255], v189 offset:3072
	s_waitcnt lgkmcnt(2)
	v_mfma_f32_32x32x16_bf16 v[160:175], v[202:205], v[244:247], v[160:175]
	ds_read_b128 v[202:205], v238 offset:32768
	ds_read_b128 v[244:247], v189 offset:7168
	s_waitcnt lgkmcnt(2)
	v_mfma_f32_32x32x16_bf16 v[144:159], v[248:251], v[252:255], v[144:159]
	s_waitcnt lgkmcnt(0)
	v_mfma_f32_32x32x16_bf16 v[160:175], v[202:205], v[244:247], v[160:175]
	ds_read_b64_tr_b16 v[202:203], v216 offset:32768
	ds_read_b64_tr_b16 v[204:205], v218 offset:32768
	ds_read_b64_tr_b16 v[244:245], v220 offset:32768
	ds_read_b64_tr_b16 v[246:247], v222 offset:32768
	ds_read_b64_tr_b16 v[248:249], v224 offset:32768
	ds_read_b64_tr_b16 v[250:251], v226 offset:32768
	ds_read_b64_tr_b16 v[252:253], v228 offset:32768
	ds_read_b64_tr_b16 v[254:255], v230 offset:32768
	s_cbranch_scc0 .Lat6_diag
.Lat6_go:
	v_sub_f32_e32 v180, v200, v199
	v_sub_f32_e32 v198, v200, v201
	s_nop 0
	v_max3_f32 v217, v144, v145, v146
	v_max3_f32 v219, v160, v161, v162
	v_max3_f32 v221, v147, v148, v149
	v_max3_f32 v225, v163, v164, v165
	v_max3_f32 v223, v150, v151, v152
	v_max3_f32 v229, v166, v167, v168
	v_add_f32_e32 v144, v144, v180
	v_add_f32_e32 v160, v160, v198
	v_max3_f32 v217, v217, v221, v223
	v_exp_f32_e32 v144, v144
	v_exp_f32_e32 v160, v160
	v_max3_f32 v219, v219, v225, v229
	v_add_f32_e32 v145, v145, v180
	v_add_f32_e32 v161, v161, v198
	v_max3_f32 v221, v153, v154, v155
	v_exp_f32_e32 v145, v145
	v_exp_f32_e32 v161, v161
	v_max3_f32 v225, v169, v170, v171
	v_add_f32_e32 v146, v146, v180
	v_add_f32_e32 v162, v162, v198
	v_max3_f32 v223, v156, v157, v158
	v_exp_f32_e32 v146, v146
	v_exp_f32_e32 v162, v162
	v_max3_f32 v229, v172, v173, v174
	v_add_f32_e32 v147, v147, v180
	v_add_f32_e32 v163, v163, v198
	v_max3_f32 v221, v221, v223, v159
	v_exp_f32_e32 v147, v147
	v_exp_f32_e32 v163, v163
	v_max3_f32 v225, v225, v229, v175
	v_add_f32_e32 v148, v148, v180
	v_add_f32_e32 v164, v164, v198
	v_max_f32_e32 v217, v217, v221
	v_exp_f32_e32 v148, v148
	v_exp_f32_e32 v164, v164
	v_max_f32_e32 v219, v219, v225
	v_add_f32_e32 v149, v149, v180
	v_add_f32_e32 v165, v165, v198
	v_add_f32_e32 v221, v200, v217
	v_exp_f32_e32 v149, v149
	v_exp_f32_e32 v165, v165
	v_add_f32_e32 v225, v200, v219
	v_add_f32_e32 v150, v150, v180
	v_add_f32_e32 v166, v166, v198
	v_cmp_gt_f32_e32 vcc, v221, v227
	v_exp_f32_e32 v150, v150
	v_exp_f32_e32 v166, v166
	v_cmp_gt_f32_e64 s[0:1], v225, v215
	v_sub_f32_e32 v223, v221, v227
	v_sub_f32_e32 v229, v225, v215
	v_max_f32_e32 v223, v223, v229
	v_add_f32_e32 v223, 0x43280000, v223
	v_cmp_nlt_f32_e64 s[98:99], v223, 0
	v_add_f32_e32 v151, v151, v180
	v_add_f32_e32 v167, v167, v198
	v_exp_f32_e32 v151, v151
	v_exp_f32_e32 v167, v167
	v_add_f32_e32 v215, v144, v145
	v_add_f32_e32 v217, v160, v161
	v_add_f32_e32 v215, v215, v146
	v_add_f32_e32 v217, v217, v162
	v_add_f32_e32 v215, v215, v147
	v_add_f32_e32 v217, v217, v163
	v_add_f32_e32 v215, v215, v148
	v_add_f32_e32 v217, v217, v164
	v_add_f32_e32 v215, v215, v149
	v_add_f32_e32 v217, v217, v165
	v_add_f32_e32 v215, v215, v150
	v_add_f32_e32 v217, v217, v166
	v_add_f32_e32 v215, v215, v151
	v_add_f32_e32 v217, v217, v167
	v_cvt_pk_bf16_f32 v144, v144, v145
	v_cvt_pk_bf16_f32 v160, v160, v161
	v_cvt_pk_bf16_f32 v145, v146, v147
	v_cvt_pk_bf16_f32 v161, v162, v163
	v_cvt_pk_bf16_f32 v146, v148, v149
	v_cvt_pk_bf16_f32 v162, v164, v165
	v_cvt_pk_bf16_f32 v147, v150, v151
	v_cvt_pk_bf16_f32 v163, v166, v167
	ds_read_b64_tr_b16 v[148:149], v216 offset:36864
	ds_read_b64_tr_b16 v[150:151], v218 offset:36864
	ds_read_b64_tr_b16 v[164:165], v220 offset:36864
	ds_read_b64_tr_b16 v[166:167], v222 offset:36864
	s_or_b64 vcc, vcc, s[0:1]
	s_cbranch_vccnz .Lat6_redo
	s_cmp_eq_u64 s[98:99], 0
	s_cselect_b32 s51, 1, 0
	s_cbranch_scc1 .Lat6_skip
	s_waitcnt lgkmcnt(4)
	v_mfma_f32_32x32x16_bf16 v[112:127], v[202:205], v[144:147], v[112:127]
	v_add_f32_e32 v152, v152, v180
	v_add_f32_e32 v168, v168, v198
	v_exp_f32_e32 v152, v152
	v_exp_f32_e32 v168, v168
	v_mfma_f32_32x32x16_bf16 v[96:111], v[202:205], v[160:163], v[96:111]
	v_add_f32_e32 v153, v153, v180
	v_add_f32_e32 v169, v169, v198
	v_exp_f32_e32 v153, v153
	v_exp_f32_e32 v169, v169
	ds_read_b64_tr_b16 v[202:203], v224 offset:36864
	ds_read_b64_tr_b16 v[204:205], v226 offset:36864
	v_mfma_f32_32x32x16_bf16 v[64:79], v[244:247], v[144:147], v[64:79]
	v_add_f32_e32 v154, v154, v180
	v_add_f32_e32 v170, v170, v198
	v_exp_f32_e32 v154, v154
	v_exp_f32_e32 v170, v170
	v_mfma_f32_32x32x16_bf16 v[80:95], v[244:247], v[160:163], v[80:95]
	v_add_f32_e32 v155, v155, v180
	v_add_f32_e32 v171, v171, v198
	v_exp_f32_e32 v155, v155
	v_exp_f32_e32 v171, v171
	ds_read_b64_tr_b16 v[244:245], v228 offset:36864
	ds_read_b64_tr_b16 v[246:247], v230 offset:36864
	v_mfma_f32_32x32x16_bf16 v[32:47], v[248:251], v[144:147], v[32:47]
	v_add_f32_e32 v156, v156, v180
	v_add_f32_e32 v172, v172, v198
	v_exp_f32_e32 v156, v156
	v_exp_f32_e32 v172, v172
	v_mfma_f32_32x32x16_bf16 v[48:63], v[248:251], v[160:163], v[48:63]
	v_add_f32_e32 v157, v157, v180
	v_add_f32_e32 v173, v173, v198
	v_exp_f32_e32 v157, v157
	v_exp_f32_e32 v173, v173
	v_mfma_f32_32x32x16_bf16 v[0:15], v[252:255], v[144:147], v[0:15]
	v_add_f32_e32 v158, v158, v180
	v_add_f32_e32 v174, v174, v198
	v_exp_f32_e32 v158, v158
	v_exp_f32_e32 v174, v174
	v_mfma_f32_32x32x16_bf16 v[16:31], v[252:255], v[160:163], v[16:31]
	v_add_f32_e32 v159, v159, v180
	v_add_f32_e32 v175, v175, v198
	v_exp_f32_e32 v159, v159
	v_exp_f32_e32 v175, v175
	v_cvt_pk_bf16_f32 v248, v152, v153
	v_cvt_pk_bf16_f32 v252, v168, v169
	v_cvt_pk_bf16_f32 v249, v154, v155
	v_cvt_pk_bf16_f32 v253, v170, v171
	v_cvt_pk_bf16_f32 v250, v156, v157
	v_cvt_pk_bf16_f32 v254, v172, v173
	v_cvt_pk_bf16_f32 v251, v158, v159
	v_cvt_pk_bf16_f32 v255, v174, v175
	s_nop 0
	s_waitcnt lgkmcnt(6)
	v_mfma_f32_32x32x16_bf16 v[112:127], v[148:151], v[248:251], v[112:127]
	v_add_f32_e32 v215, v215, v152
	v_add_f32_e32 v217, v217, v168
	v_mfma_f32_32x32x16_bf16 v[96:111], v[148:151], v[252:255], v[96:111]
	v_add_f32_e32 v215, v215, v153
	v_add_f32_e32 v217, v217, v169
	v_add_f32_e32 v215, v215, v154
	s_waitcnt lgkmcnt(4)
	v_mfma_f32_32x32x16_bf16 v[64:79], v[164:167], v[248:251], v[64:79]
	v_add_f32_e32 v217, v217, v170
	v_add_f32_e32 v215, v215, v155
	v_mfma_f32_32x32x16_bf16 v[80:95], v[164:167], v[252:255], v[80:95]
	v_add_f32_e32 v217, v217, v171
	v_add_f32_e32 v215, v215, v156
	v_add_f32_e32 v217, v217, v172
	s_waitcnt lgkmcnt(2)
	v_mfma_f32_32x32x16_bf16 v[32:47], v[202:205], v[248:251], v[32:47]
	v_add_f32_e32 v215, v215, v157
	v_add_f32_e32 v217, v217, v173
	v_mfma_f32_32x32x16_bf16 v[48:63], v[202:205], v[252:255], v[48:63]
	v_add_f32_e32 v215, v215, v158
	v_add_f32_e32 v217, v217, v174
	v_add_f32_e32 v215, v215, v159
	s_waitcnt lgkmcnt(0)
	v_mfma_f32_32x32x16_bf16 v[0:15], v[244:247], v[248:251], v[0:15]
	v_add_f32_e32 v217, v217, v175
	v_add_f32_e32 v197, v197, v215
	v_mfma_f32_32x32x16_bf16 v[16:31], v[244:247], v[252:255], v[16:31]
	v_add_f32_e32 v196, v196, v217

.Lat1_probe:
	ds_read_b128 v[160:163], v237 offset:8192
	ds_read_b128 v[164:167], v189
	ds_read_b128 v[202:205], v235 offset:8192
	ds_read_b128 v[244:247], v189 offset:4096
	ds_read_b128 v[248:251], v236 offset:8192
	ds_read_b128 v[252:255], v189 offset:1024
	s_waitcnt lgkmcnt(4)
	v_mfma_f32_32x32x16_bf16 v[144:159], v[160:163], v[164:167], v[128:143]
	s_waitcnt lgkmcnt(2)
	v_mfma_f32_32x32x16_bf16 v[160:175], v[202:205], v[244:247], v[128:143]
	ds_read_b128 v[202:205], v234 offset:8192
	ds_read_b128 v[244:247], v189 offset:5120
	v_add_u32_e32 v215, s40, v185
	v_add_u32_e32 v215, 0xe0, v215
	v_cvt_f32_i32_e32 v215, v215
	v_add_f32_e32 v227, 0x41000000, v199
	v_mul_f32_e32 v200, v184, v215
	v_add_f32_e32 v215, 0x41000000, v201
	s_waitcnt lgkmcnt(2)
	v_mfma_f32_32x32x16_bf16 v[144:159], v[248:251], v[252:255], v[144:159]
	ds_read_b128 v[248:251], v241 offset:8192
	ds_read_b128 v[252:255], v189 offset:2048
	s_waitcnt lgkmcnt(2)
	v_mfma_f32_32x32x16_bf16 v[160:175], v[202:205], v[244:247], v[160:175]
	ds_read_b128 v[202:205], v239 offset:8192
	ds_read_b128 v[244:247], v189 offset:6144
	s_waitcnt lgkmcnt(2)
	v_mfma_f32_32x32x16_bf16 v[144:159], v[248:251], v[252:255], v[144:159]
	ds_read_b128 v[248:251], v240 offset:8192
	ds_read_b128 v[252:255], v189 offset:3072
	s_waitcnt lgkmcnt(2)
	v_mfma_f32_32x32x16_bf16 v[160:175], v[202:205], v[244:247], v[160:175]
	ds_read_b128 v[202:205], v238 offset:8192
	ds_read_b128 v[244:247], v189 offset:7168
	s_waitcnt lgkmcnt(2)
	v_mfma_f32_32x32x16_bf16 v[144:159], v[248:251], v[252:255], v[144:159]
	s_waitcnt lgkmcnt(0)
	v_mfma_f32_32x32x16_bf16 v[160:175], v[202:205], v[244:247], v[160:175]
	s_nop 7
	s_nop 7
	v_max3_f32 v217, v144, v145, v146
	v_max3_f32 v219, v160, v161, v162
	v_max3_f32 v221, v147, v148, v149
	v_max3_f32 v225, v163, v164, v165
	v_max3_f32 v223, v150, v151, v152
	v_max3_f32 v229, v166, v167, v168
	v_max3_f32 v217, v217, v221, v223
	v_max3_f32 v219, v219, v225, v229
	v_max3_f32 v221, v153, v154, v155
	v_max3_f32 v225, v169, v170, v171
	v_max3_f32 v223, v156, v157, v158
	v_max3_f32 v229, v172, v173, v174
	v_max3_f32 v221, v221, v223, v159
	v_max3_f32 v225, v225, v229, v175
	v_max_f32_e32 v217, v217, v221
	v_max_f32_e32 v219, v219, v225
	v_add_f32_e32 v221, v200, v217
	v_add_f32_e32 v225, v200, v219
	v_sub_f32_e32 v223, v221, v227
	v_sub_f32_e32 v229, v225, v215
	v_max_f32_e32 v223, v223, v229
	v_add_f32_e32 v223, 0x43280000, v223
	v_cmp_nlt_f32_e64 s[98:99], v223, 0
	s_nop 3
	s_cmp_eq_u64 s[98:99], 0
	s_cbranch_scc1 .Lat1_skip
	s_mov_b32 s51, 0
	s_branch .Lat1_redo
.Lat2_probe:
	ds_read_b128 v[160:163], v237
	ds_read_b128 v[164:167], v189
	ds_read_b128 v[202:205], v235
	ds_read_b128 v[244:247], v189 offset:4096
	ds_read_b128 v[248:251], v236
	ds_read_b128 v[252:255], v189 offset:1024
	s_waitcnt lgkmcnt(4)
	v_mfma_f32_32x32x16_bf16 v[144:159], v[160:163], v[164:167], v[128:143]
	s_waitcnt lgkmcnt(2)
	v_mfma_f32_32x32x16_bf16 v[160:175], v[202:205], v[244:247], v[128:143]
	ds_read_b128 v[202:205], v234
	ds_read_b128 v[244:247], v189 offset:5120
	v_add_u32_e32 v215, s40, v185
	v_add_u32_e32 v215, 0xc0, v215
	v_cvt_f32_i32_e32 v215, v215
	v_add_f32_e32 v227, 0x41000000, v199
	v_mul_f32_e32 v200, v184, v215
	v_add_f32_e32 v215, 0x41000000, v201
	s_waitcnt lgkmcnt(2)
	v_mfma_f32_32x32x16_bf16 v[144:159], v[248:251], v[252:255], v[144:159]
	ds_read_b128 v[248:251], v241
	ds_read_b128 v[252:255], v189 offset:2048
	s_waitcnt lgkmcnt(2)
	v_mfma_f32_32x32x16_bf16 v[160:175], v[202:205], v[244:247], v[160:175]
	ds_read_b128 v[202:205], v239
	ds_read_b128 v[244:247], v189 offset:6144
	s_waitcnt lgkmcnt(2)
	v_mfma_f32_32x32x16_bf16 v[144:159], v[248:251], v[252:255], v[144:159]
	ds_read_b128 v[248:251], v240
	ds_read_b128 v[252:255], v189 offset:3072
	s_waitcnt lgkmcnt(2)
	v_mfma_f32_32x32x16_bf16 v[160:175], v[202:205], v[244:247], v[160:175]
	ds_read_b128 v[202:205], v238
	ds_read_b128 v[244:247], v189 offset:7168
	s_waitcnt lgkmcnt(2)
	v_mfma_f32_32x32x16_bf16 v[144:159], v[248:251], v[252:255], v[144:159]
	s_waitcnt lgkmcnt(0)
	v_mfma_f32_32x32x16_bf16 v[160:175], v[202:205], v[244:247], v[160:175]
	s_nop 7
	s_nop 7
	v_max3_f32 v217, v144, v145, v146
	v_max3_f32 v219, v160, v161, v162
	v_max3_f32 v221, v147, v148, v149
	v_max3_f32 v225, v163, v164, v165
	v_max3_f32 v223, v150, v151, v152
	v_max3_f32 v229, v166, v167, v168
	v_max3_f32 v217, v217, v221, v223
	v_max3_f32 v219, v219, v225, v229
	v_max3_f32 v221, v153, v154, v155
	v_max3_f32 v225, v169, v170, v171
	v_max3_f32 v223, v156, v157, v158
	v_max3_f32 v229, v172, v173, v174
	v_max3_f32 v221, v221, v223, v159
	v_max3_f32 v225, v225, v229, v175
	v_max_f32_e32 v217, v217, v221
	v_max_f32_e32 v219, v219, v225
	v_add_f32_e32 v221, v200, v217
	v_add_f32_e32 v225, v200, v219
	v_sub_f32_e32 v223, v221, v227
	v_sub_f32_e32 v229, v225, v215
	v_max_f32_e32 v223, v223, v229
	v_add_f32_e32 v223, 0x43280000, v223
	v_cmp_nlt_f32_e64 s[98:99], v223, 0
	s_nop 3
	s_cmp_eq_u64 s[98:99], 0
	s_cbranch_scc1 .Lat2_skip
	s_mov_b32 s51, 0
	s_branch .Lat2_redo
.Lat3_probe:
	ds_read_b128 v[160:163], v237 offset:24576
	ds_read_b128 v[164:167], v189
	ds_read_b128 v[202:205], v235 offset:24576
	ds_read_b128 v[244:247], v189 offset:4096
	ds_read_b128 v[248:251], v236 offset:24576
	ds_read_b128 v[252:255], v189 offset:1024
	s_waitcnt lgkmcnt(4)
	v_mfma_f32_32x32x16_bf16 v[144:159], v[160:163], v[164:167], v[128:143]
	s_waitcnt lgkmcnt(2)
	v_mfma_f32_32x32x16_bf16 v[160:175], v[202:205], v[244:247], v[128:143]
	ds_read_b128 v[202:205], v234 offset:24576
	ds_read_b128 v[244:247], v189 offset:5120
	v_add_u32_e32 v215, s40, v185
	v_add_u32_e32 v215, 0xa0, v215
	v_cvt_f32_i32_e32 v215, v215
	v_add_f32_e32 v227, 0x41000000, v199
	v_mul_f32_e32 v200, v184, v215
	v_add_f32_e32 v215, 0x41000000, v201
	s_waitcnt lgkmcnt(2)
	v_mfma_f32_32x32x16_bf16 v[144:159], v[248:251], v[252:255], v[144:159]
	ds_read_b128 v[248:251], v241 offset:24576
	ds_read_b128 v[252:255], v189 offset:2048
	s_waitcnt lgkmcnt(2)
	v_mfma_f32_32x32x16_bf16 v[160:175], v[202:205], v[244:247], v[160:175]
	ds_read_b128 v[202:205], v239 offset:24576
	ds_read_b128 v[244:247], v189 offset:6144
	s_waitcnt lgkmcnt(2)
	v_mfma_f32_32x32x16_bf16 v[144:159], v[248:251], v[252:255], v[144:159]
	ds_read_b128 v[248:251], v240 offset:24576
	ds_read_b128 v[252:255], v189 offset:3072
	s_waitcnt lgkmcnt(2)
	v_mfma_f32_32x32x16_bf16 v[160:175], v[202:205], v[244:247], v[160:175]
	ds_read_b128 v[202:205], v238 offset:24576
	ds_read_b128 v[244:247], v189 offset:7168
	s_waitcnt lgkmcnt(2)
	v_mfma_f32_32x32x16_bf16 v[144:159], v[248:251], v[252:255], v[144:159]
	s_waitcnt lgkmcnt(0)
	v_mfma_f32_32x32x16_bf16 v[160:175], v[202:205], v[244:247], v[160:175]
	s_nop 7
	s_nop 7
	v_max3_f32 v217, v144, v145, v146
	v_max3_f32 v219, v160, v161, v162
	v_max3_f32 v221, v147, v148, v149
	v_max3_f32 v225, v163, v164, v165
	v_max3_f32 v223, v150, v151, v152
	v_max3_f32 v229, v166, v167, v168
	v_max3_f32 v217, v217, v221, v223
	v_max3_f32 v219, v219, v225, v229
	v_max3_f32 v221, v153, v154, v155
	v_max3_f32 v225, v169, v170, v171
	v_max3_f32 v223, v156, v157, v158
	v_max3_f32 v229, v172, v173, v174
	v_max3_f32 v221, v221, v223, v159
	v_max3_f32 v225, v225, v229, v175
	v_max_f32_e32 v217, v217, v221
	v_max_f32_e32 v219, v219, v225
	v_add_f32_e32 v221, v200, v217
	v_add_f32_e32 v225, v200, v219
	v_sub_f32_e32 v223, v221, v227
	v_sub_f32_e32 v229, v225, v215
	v_max_f32_e32 v223, v223, v229
	v_add_f32_e32 v223, 0x43280000, v223
	v_cmp_nlt_f32_e64 s[98:99], v223, 0
	s_nop 3
	s_cmp_eq_u64 s[98:99], 0
	s_cbranch_scc1 .Lat3_skip
	s_mov_b32 s51, 0
	s_branch .Lat3_redo
.Lat4_probe:
	ds_read_b128 v[160:163], v237 offset:16384
	ds_read_b128 v[164:167], v189
	ds_read_b128 v[202:205], v235 offset:16384
	ds_read_b128 v[244:247], v189 offset:4096
	ds_read_b128 v[248:251], v236 offset:16384
	ds_read_b128 v[252:255], v189 offset:1024
	s_waitcnt lgkmcnt(4)
	v_mfma_f32_32x32x16_bf16 v[144:159], v[160:163], v[164:167], v[128:143]
	s_waitcnt lgkmcnt(2)
	v_mfma_f32_32x32x16_bf16 v[160:175], v[202:205], v[244:247], v[128:143]
	ds_read_b128 v[202:205], v234 offset:16384
	ds_read_b128 v[244:247], v189 offset:5120
	v_add_u32_e32 v215, s40, v185
	v_add_u32_e32 v215, 0x80, v215
	v_cvt_f32_i32_e32 v215, v215
	v_add_f32_e32 v227, 0x41000000, v199
	v_mul_f32_e32 v200, v184, v215
	v_add_f32_e32 v215, 0x41000000, v201
	s_waitcnt lgkmcnt(2)
	v_mfma_f32_32x32x16_bf16 v[144:159], v[248:251], v[252:255], v[144:159]
	ds_read_b128 v[248:251], v241 offset:16384
	ds_read_b128 v[252:255], v189 offset:2048
	s_waitcnt lgkmcnt(2)
	v_mfma_f32_32x32x16_bf16 v[160:175], v[202:205], v[244:247], v[160:175]
	ds_read_b128 v[202:205], v239 offset:16384
	ds_read_b128 v[244:247], v189 offset:6144
	s_waitcnt lgkmcnt(2)
	v_mfma_f32_32x32x16_bf16 v[144:159], v[248:251], v[252:255], v[144:159]
	ds_read_b128 v[248:251], v240 offset:16384
	ds_read_b128 v[252:255], v189 offset:3072
	s_waitcnt lgkmcnt(2)
	v_mfma_f32_32x32x16_bf16 v[160:175], v[202:205], v[244:247], v[160:175]
	ds_read_b128 v[202:205], v238 offset:16384
	ds_read_b128 v[244:247], v189 offset:7168
	s_waitcnt lgkmcnt(2)
	v_mfma_f32_32x32x16_bf16 v[144:159], v[248:251], v[252:255], v[144:159]
	s_waitcnt lgkmcnt(0)
	v_mfma_f32_32x32x16_bf16 v[160:175], v[202:205], v[244:247], v[160:175]
	s_nop 7
	s_nop 7
	v_max3_f32 v217, v144, v145, v146
	v_max3_f32 v219, v160, v161, v162
	v_max3_f32 v221, v147, v148, v149
	v_max3_f32 v225, v163, v164, v165
	v_max3_f32 v223, v150, v151, v152
	v_max3_f32 v229, v166, v167, v168
	v_max3_f32 v217, v217, v221, v223
	v_max3_f32 v219, v219, v225, v229
	v_max3_f32 v221, v153, v154, v155
	v_max3_f32 v225, v169, v170, v171
	v_max3_f32 v223, v156, v157, v158
	v_max3_f32 v229, v172, v173, v174
	v_max3_f32 v221, v221, v223, v159
	v_max3_f32 v225, v225, v229, v175
	v_max_f32_e32 v217, v217, v221
	v_max_f32_e32 v219, v219, v225
	v_add_f32_e32 v221, v200, v217
	v_add_f32_e32 v225, v200, v219
	v_sub_f32_e32 v223, v221, v227
	v_sub_f32_e32 v229, v225, v215
	v_max_f32_e32 v223, v223, v229
	v_add_f32_e32 v223, 0x43280000, v223
	v_cmp_nlt_f32_e64 s[98:99], v223, 0
	s_nop 3
	s_cmp_eq_u64 s[98:99], 0
	s_cbranch_scc1 .Lat4_skip
	s_mov_b32 s51, 0
	s_branch .Lat4_redo
.Lat5_probe:
	ds_read_b128 v[160:163], v237 offset:40960
	ds_read_b128 v[164:167], v189
	ds_read_b128 v[202:205], v235 offset:40960
	ds_read_b128 v[244:247], v189 offset:4096
	ds_read_b128 v[248:251], v236 offset:40960
	ds_read_b128 v[252:255], v189 offset:1024
	s_waitcnt lgkmcnt(4)
	v_mfma_f32_32x32x16_bf16 v[144:159], v[160:163], v[164:167], v[128:143]
	s_waitcnt lgkmcnt(2)
	v_mfma_f32_32x32x16_bf16 v[160:175], v[202:205], v[244:247], v[128:143]
	ds_read_b128 v[202:205], v234 offset:40960
	ds_read_b128 v[244:247], v189 offset:5120
	v_add_u32_e32 v215, s40, v185
	v_add_u32_e32 v215, 0x60, v215
	v_cvt_f32_i32_e32 v215, v215
	v_add_f32_e32 v227, 0x41000000, v199
	v_mul_f32_e32 v200, v184, v215
	v_add_f32_e32 v215, 0x41000000, v201
	s_waitcnt lgkmcnt(2)
	v_mfma_f32_32x32x16_bf16 v[144:159], v[248:251], v[252:255], v[144:159]
	ds_read_b128 v[248:251], v241 offset:40960
	ds_read_b128 v[252:255], v189 offset:2048
	s_waitcnt lgkmcnt(2)
	v_mfma_f32_32x32x16_bf16 v[160:175], v[202:205], v[244:247], v[160:175]
	ds_read_b128 v[202:205], v239 offset:40960
	ds_read_b128 v[244:247], v189 offset:6144
	s_waitcnt lgkmcnt(2)
	v_mfma_f32_32x32x16_bf16 v[144:159], v[248:251], v[252:255], v[144:159]
	ds_read_b128 v[248:251], v240 offset:40960
	ds_read_b128 v[252:255], v189 offset:3072
	s_waitcnt lgkmcnt(2)
	v_mfma_f32_32x32x16_bf16 v[160:175], v[202:205], v[244:247], v[160:175]
	ds_read_b128 v[202:205], v238 offset:40960
	ds_read_b128 v[244:247], v189 offset:7168
	s_waitcnt lgkmcnt(2)
	v_mfma_f32_32x32x16_bf16 v[144:159], v[248:251], v[252:255], v[144:159]
	s_waitcnt lgkmcnt(0)
	v_mfma_f32_32x32x16_bf16 v[160:175], v[202:205], v[244:247], v[160:175]
	s_nop 7
	s_nop 7
	v_max3_f32 v217, v144, v145, v146
	v_max3_f32 v219, v160, v161, v162
	v_max3_f32 v221, v147, v148, v149
	v_max3_f32 v225, v163, v164, v165
	v_max3_f32 v223, v150, v151, v152
	v_max3_f32 v229, v166, v167, v168
	v_max3_f32 v217, v217, v221, v223
	v_max3_f32 v219, v219, v225, v229
	v_max3_f32 v221, v153, v154, v155
	v_max3_f32 v225, v169, v170, v171
	v_max3_f32 v223, v156, v157, v158
	v_max3_f32 v229, v172, v173, v174
	v_max3_f32 v221, v221, v223, v159
	v_max3_f32 v225, v225, v229, v175
	v_max_f32_e32 v217, v217, v221
	v_max_f32_e32 v219, v219, v225
	v_add_f32_e32 v221, v200, v217
	v_add_f32_e32 v225, v200, v219
	v_sub_f32_e32 v223, v221, v227
	v_sub_f32_e32 v229, v225, v215
	v_max_f32_e32 v223, v223, v229
	v_add_f32_e32 v223, 0x43280000, v223
	v_cmp_nlt_f32_e64 s[98:99], v223, 0
	s_nop 3
	s_cmp_eq_u64 s[98:99], 0
	s_cbranch_scc1 .Lat5_skip
	s_mov_b32 s51, 0
	s_branch .Lat5_redo
.Lat6_probe:
	ds_read_b128 v[160:163], v237 offset:32768
	ds_read_b128 v[164:167], v189
	ds_read_b128 v[202:205], v235 offset:32768
	ds_read_b128 v[244:247], v189 offset:4096
	ds_read_b128 v[248:251], v236 offset:32768
	ds_read_b128 v[252:255], v189 offset:1024
	s_waitcnt lgkmcnt(4)
	v_mfma_f32_32x32x16_bf16 v[144:159], v[160:163], v[164:167], v[128:143]
	s_waitcnt lgkmcnt(2)
	v_mfma_f32_32x32x16_bf16 v[160:175], v[202:205], v[244:247], v[128:143]
	ds_read_b128 v[202:205], v234 offset:32768
	ds_read_b128 v[244:247], v189 offset:5120
	v_add_u32_e32 v215, s40, v185
	v_add_u32_e32 v215, 0x40, v215
	v_cvt_f32_i32_e32 v215, v215
	v_add_f32_e32 v227, 0x41000000, v199
	v_mul_f32_e32 v200, v184, v215
	v_add_f32_e32 v215, 0x41000000, v201
	s_waitcnt lgkmcnt(2)
	v_mfma_f32_32x32x16_bf16 v[144:159], v[248:251], v[252:255], v[144:159]
	ds_read_b128 v[248:251], v241 offset:32768
	ds_read_b128 v[252:255], v189 offset:2048
	s_waitcnt lgkmcnt(2)
	v_mfma_f32_32x32x16_bf16 v[160:175], v[202:205], v[244:247], v[160:175]
	ds_read_b128 v[202:205], v239 offset:32768
	ds_read_b128 v[244:247], v189 offset:6144
	s_waitcnt lgkmcnt(2)
	v_mfma_f32_32x32x16_bf16 v[144:159], v[248:251], v[252:255], v[144:159]
	ds_read_b128 v[248:251], v240 offset:32768
	ds_read_b128 v[252:255], v189 offset:3072
	s_waitcnt lgkmcnt(2)
	v_mfma_f32_32x32x16_bf16 v[160:175], v[202:205], v[244:247], v[160:175]
	ds_read_b128 v[202:205], v238 offset:32768
	ds_read_b128 v[244:247], v189 offset:7168
	s_waitcnt lgkmcnt(2)
	v_mfma_f32_32x32x16_bf16 v[144:159], v[248:251], v[252:255], v[144:159]
	s_waitcnt lgkmcnt(0)
	v_mfma_f32_32x32x16_bf16 v[160:175], v[202:205], v[244:247], v[160:175]
	s_nop 7
	s_nop 7
	v_max3_f32 v217, v144, v145, v146
	v_max3_f32 v219, v160, v161, v162
	v_max3_f32 v221, v147, v148, v149
	v_max3_f32 v225, v163, v164, v165
	v_max3_f32 v223, v150, v151, v152
	v_max3_f32 v229, v166, v167, v168
	v_max3_f32 v217, v217, v221, v223
	v_max3_f32 v219, v219, v225, v229
	v_max3_f32 v221, v153, v154, v155
	v_max3_f32 v225, v169, v170, v171
	v_max3_f32 v223, v156, v157, v158
	v_max3_f32 v229, v172, v173, v174
	v_max3_f32 v221, v221, v223, v159
	v_max3_f32 v225, v225, v229, v175
	v_max_f32_e32 v217, v217, v221
	v_max_f32_e32 v219, v219, v225
	v_add_f32_e32 v221, v200, v217
	v_add_f32_e32 v225, v200, v219
	v_sub_f32_e32 v223, v221, v227
	v_sub_f32_e32 v229, v225, v215
	v_max_f32_e32 v223, v223, v229
	v_add_f32_e32 v223, 0x43280000, v223
	v_cmp_nlt_f32_e64 s[98:99], v223, 0
	s_nop 3
	s_cmp_eq_u64 s[98:99], 0
	s_cbranch_scc1 .Lat6_skip
	s_mov_b32 s51, 0
	s_branch .Lat6_redo
